# grid barrier: non-leader workgroups poll the cross-XCD release word directly (one hop less)
# speedup vs baseline: 1.0128x; 1.0128x over previous
.LBB0_323:
	s_or_b64 exec, exec, s[8:9]
	v_cvt_f32_u32_e32 v4, v2
	s_waitcnt vmcnt(0)
	v_readfirstlane_b32 s3, v3
	v_sub_u32_e32 v3, 0, v2
	v_rcp_iflag_f32_e32 v4, v4
	v_add_u32_e32 v5, s3, v1
	v_mul_f32_e32 v4, 0x4f7ffffe, v4
	v_cvt_u32_f32_e32 v4, v4
	v_mul_lo_u32 v1, v3, v4
	v_mul_hi_u32 v1, v4, v1
	v_add_u32_e32 v1, v4, v1
	v_mul_hi_u32 v1, v5, v1
	v_mul_lo_u32 v3, v1, v2
	v_sub_u32_e32 v3, v5, v3
	v_add_u32_e32 v4, 1, v1
	v_cmp_ge_u32_e32 vcc, v3, v2
	s_nop 1
	v_cndmask_b32_e32 v1, v1, v4, vcc
	v_sub_u32_e32 v4, v3, v2
	v_cndmask_b32_e32 v3, v3, v4, vcc
	v_add_u32_e32 v4, 1, v1
	v_cmp_ge_u32_e32 vcc, v3, v2
	v_add_u32_e32 v3, 1, v5
	s_nop 0
	v_cndmask_b32_e32 v1, v1, v4, vcc
	v_mul_lo_u32 v4, v2, v1
	v_add_u32_e32 v2, v4, v2
	v_cmp_ne_u32_e32 vcc, v3, v2
	s_and_saveexec_b64 s[6:7], vcc
	s_xor_b64 s[6:7], exec, s[6:7]
	s_cbranch_execz .LBB0_337
	s_waitcnt lgkmcnt(0)
	v_mov_b32_e32 v0, 0x3500
	buffer_inv sc1
	global_load_dword v0, v0, s[38:39] sc1
	s_add_u32 s10, s38, 0x3500
	s_addc_u32 s11, s39, 0
	s_waitcnt vmcnt(0)
	v_cmp_eq_u32_e32 vcc, v0, v1
	s_and_saveexec_b64 s[8:9], vcc
	s_cbranch_execz .LBB0_336
	s_mov_b32 s3, 1
	s_mov_b64 s[12:13], 0
	v_mov_b32_e32 v0, 0
	s_branch .LBB0_327

.LBB0_1637:
	s_or_b64 exec, exec, s[12:13]
	v_cvt_f32_u32_e32 v4, v2
	s_waitcnt vmcnt(0)
	v_readfirstlane_b32 s3, v3
	v_sub_u32_e32 v3, 0, v2
	v_rcp_iflag_f32_e32 v4, v4
	v_add_u32_e32 v5, s3, v1
	v_mul_f32_e32 v4, 0x4f7ffffe, v4
	v_cvt_u32_f32_e32 v4, v4
	v_mul_lo_u32 v1, v3, v4
	v_mul_hi_u32 v1, v4, v1
	v_add_u32_e32 v1, v4, v1
	v_mul_hi_u32 v1, v5, v1
	v_mul_lo_u32 v3, v1, v2
	v_sub_u32_e32 v3, v5, v3
	v_add_u32_e32 v4, 1, v1
	v_cmp_ge_u32_e32 vcc, v3, v2
	s_nop 1
	v_cndmask_b32_e32 v1, v1, v4, vcc
	v_sub_u32_e32 v4, v3, v2
	v_cndmask_b32_e32 v3, v3, v4, vcc
	v_add_u32_e32 v4, 1, v1
	v_cmp_ge_u32_e32 vcc, v3, v2
	v_add_u32_e32 v3, 1, v5
	s_nop 0
	v_cndmask_b32_e32 v1, v1, v4, vcc
	v_mul_lo_u32 v4, v2, v1
	v_add_u32_e32 v2, v4, v2
	v_cmp_ne_u32_e32 vcc, v3, v2
	s_and_saveexec_b64 s[6:7], vcc
	s_xor_b64 s[6:7], exec, s[6:7]
	s_cbranch_execz .LBB0_1651
	s_waitcnt lgkmcnt(0)
	v_mov_b32_e32 v0, 0x3500
	buffer_inv sc1
	global_load_dword v0, v0, s[38:39] sc1
	s_add_u32 s14, s38, 0x3500
	s_addc_u32 s15, s39, 0
	s_waitcnt vmcnt(0)
	v_cmp_eq_u32_e32 vcc, v0, v1
	s_and_saveexec_b64 s[12:13], vcc
	s_cbranch_execz .LBB0_1650
	s_mov_b32 s3, 1
	s_mov_b64 s[16:17], 0
	v_mov_b32_e32 v0, 0
	s_branch .LBB0_1641

.LBB0_1874:
	s_or_b64 exec, exec, s[6:7]
	v_cvt_f32_u32_e32 v4, v2
	s_waitcnt vmcnt(0)
	v_readfirstlane_b32 s4, v3
	v_sub_u32_e32 v3, 0, v2
	v_rcp_iflag_f32_e32 v4, v4
	v_add_u32_e32 v5, s4, v1
	v_mul_f32_e32 v4, 0x4f7ffffe, v4
	v_cvt_u32_f32_e32 v4, v4
	v_mul_lo_u32 v1, v3, v4
	v_mul_hi_u32 v1, v4, v1
	v_add_u32_e32 v1, v4, v1
	v_mul_hi_u32 v1, v5, v1
	v_mul_lo_u32 v3, v1, v2
	v_sub_u32_e32 v3, v5, v3
	v_add_u32_e32 v4, 1, v1
	v_cmp_ge_u32_e32 vcc, v3, v2
	s_nop 1
	v_cndmask_b32_e32 v1, v1, v4, vcc
	v_sub_u32_e32 v4, v3, v2
	v_cndmask_b32_e32 v3, v3, v4, vcc
	v_add_u32_e32 v4, 1, v1
	v_cmp_ge_u32_e32 vcc, v3, v2
	v_add_u32_e32 v3, 1, v5
	s_nop 0
	v_cndmask_b32_e32 v1, v1, v4, vcc
	v_mul_lo_u32 v4, v2, v1
	v_add_u32_e32 v2, v4, v2
	v_cmp_ne_u32_e32 vcc, v3, v2
	s_and_saveexec_b64 s[4:5], vcc
	s_xor_b64 s[4:5], exec, s[4:5]
	s_cbranch_execz .LBB0_1888
	s_waitcnt lgkmcnt(0)
	v_mov_b32_e32 v0, 0x3500
	buffer_inv sc1
	global_load_dword v0, v0, s[38:39] sc1
	s_add_u32 s10, s38, 0x3500
	s_addc_u32 s11, s39, 0
	s_waitcnt vmcnt(0)
	v_cmp_eq_u32_e32 vcc, v0, v1
	s_and_saveexec_b64 s[6:7], vcc
	s_cbranch_execz .LBB0_1887
	s_mov_b32 s24, 1
	s_mov_b64 s[12:13], 0
	v_mov_b32_e32 v0, 0
	s_branch .LBB0_1878
